# v33 plus 64-byte alignment (.p2align 6) of the five GEMM K-loop heads and the GQA tile loop head (code placement)
# baseline (speedup 1.0000x reference)
; DI int opaque_tid() { int t = threadIdx.x; asm volatile("" : "+v"(t)); return t; }
; #define WAIT_V(n) asm volatile("s_waitcnt vmcnt(" #n ")" ::: "memory")
; #define WAIT_L(n) asm volatile("s_waitcnt lgkmcnt(" #n ")" ::: "memory")
; #define BAR __builtin_amdgcn_s_barrier()
; #define SCHED __builtin_amdgcn_sched_barrier(0)
;     ...
;     const bool has_next = unit(ui + 1, npm, npn, nkq);
;     const char* nA = has_next ? (const char*)A + (size_t)npm * tstep + (nkq > 0 ? (size_t)nkq * (K / 4) * 2 : 0) : cA;
;     const char* nB = has_next ? (const char*)Bt + (size_t)npn * tstep + (nkq > 0 ? (size_t)nkq * (K / 4) * 2 : 0) : cB;
;     const int ntu = (SPLIT && kq >= 0) ? nt / 4 : nt;
;     for (int t = 0; t < ntu; t += 2) {
;       const bool last = (t == ntu - 2);
;       const char* a1 = cA + (size_t)(t + 1) * kstep;
;       const char* a2 = last ? nA : cA + (size_t)(t + 2) * kstep;
;       const char* b2 = last ? nB : cB + (size_t)(t + 2) * kstep;
;       const char* a3 = a2 + kstep;
;       const char* b3 = b2 + kstep;
;       LDB(B0, 0, 0); LDB(B1, 0, 1); SCHED; LDA(At, 0, 0); STAGE(SAo(1, 1), a1 + hstep, voff);
;       WAIT_V(8); WAIT_L(0); BAR; MMA(0, 0, At, B0); MMA(0, 1, At, B1); BAR; SCHED;
;       LDA(At, 0, 1); STAGE(SBo(0, 0), b2, voffB); STAGE(SBo(0, 1), b2 + hstep, voffB); STAGE(SAo(0, 0), a2, voff);
;       WAIT_V(8); WAIT_L(0); BAR; MMA(1, 0, At, B0); MMA(1, 1, At, B1); BAR; SCHED;
;       LDB(B0, 1, 0); LDB(B1, 1, 1); SCHED; LDA(At, 1, 0); STAGE(SAo(0, 1), a2 + hstep, voff);
;       WAIT_V(8); WAIT_L(0); BAR; MMA(0, 0, At, B0); MMA(0, 1, At, B1); BAR; SCHED;
;       LDA(At, 1, 1); STAGE(SBo(1, 0), b3, voffB); STAGE(SBo(1, 1), b3 + hstep, voffB); STAGE(SAo(1, 0), a3, voff);
;       WAIT_V(8); WAIT_L(0); BAR; MMA(1, 0, At, B0); MMA(1, 1, At, B1); BAR; SCHED;
;     }
;     if (wr == 0) BAR;
;     {
;       const int tid2 = opaque_tid(), lane2 = tid2 & 63;
;       gemm_epilogue<EPI>(p, layer, acc, pm * BM, pn * BM, pn, wr, wc, lane2 & 15, lane2 >> 4, (char*)shm + XCH_OFF, SPLIT ? kq : -1);
;     }
;     if (!has_next) break;
; #pragma unroll
;     for (int a = 0; a < 2; ++a)
; #pragma unroll
;       for (int b = 0; b < 2; ++b)
; #pragma unroll
;         for (int m = 0; m < 4; ++m)
; #pragma unroll
;           for (int n = 0; n < 2; ++n) acc[a][b][m][n] = (f32x4){0.f, 0.f, 0.f, 0.f};
.LBB0_151:
	s_nop 0
	v_readlane_b32 s26, v254, 34
	v_readlane_b32 s27, v254, 35
	v_readlane_b32 s60, v254, 45
	s_lshl_b64 s[4:5], s[26:27], 19
	v_readlane_b32 s74, v254, 59
	v_readlane_b32 s75, v254, 60
	s_add_u32 s50, s74, s4
	s_addc_u32 s51, s75, s5
	s_and_b64 s[4:5], s[36:37], exec
	s_mov_b32 s49, s27
	s_cselect_b32 s22, s51, s1
	s_cselect_b32 s25, s50, s0
	s_lshl_b64 s[4:5], s[48:49], 19
	s_add_u32 s52, s6, s4
	s_addc_u32 s53, s7, s5
	s_and_b64 s[4:5], s[36:37], exec
	s_cselect_b32 s26, s53, s3
	s_cselect_b32 s27, s52, s2
	s_add_u32 s0, s0, 0x40080
	s_addc_u32 s1, s1, 0
	s_add_u32 s28, s2, 0x100
	v_mov_b32_e32 v2, 0
	s_addc_u32 s29, s3, 0
	s_mov_b32 s30, -2
	v_mov_b32_e32 v3, v2
	v_mov_b32_e32 v4, v2
	v_mov_b32_e32 v5, v2
	v_mov_b32_e32 v6, v2
	v_mov_b32_e32 v7, v2
	v_mov_b32_e32 v8, v2
	v_mov_b32_e32 v9, v2
	v_mov_b32_e32 v18, v2
	v_mov_b32_e32 v19, v2
	v_mov_b32_e32 v20, v2
	v_mov_b32_e32 v21, v2
	v_mov_b32_e32 v22, v2
	v_mov_b32_e32 v23, v2
	v_mov_b32_e32 v24, v2
	v_mov_b32_e32 v25, v2
	v_mov_b32_e32 v34, v2
	v_mov_b32_e32 v35, v2
	v_mov_b32_e32 v36, v2
	v_mov_b32_e32 v37, v2
	v_mov_b32_e32 v38, v2
	v_mov_b32_e32 v39, v2
	v_mov_b32_e32 v40, v2
	v_mov_b32_e32 v41, v2
	v_mov_b32_e32 v50, v2
	v_mov_b32_e32 v51, v2
	v_mov_b32_e32 v52, v2
	v_mov_b32_e32 v53, v2
	v_mov_b32_e32 v54, v2
	v_mov_b32_e32 v55, v2
	v_mov_b32_e32 v56, v2
	v_mov_b32_e32 v57, v2
	v_mov_b32_e32 v10, v2
	v_mov_b32_e32 v11, v2
	v_mov_b32_e32 v12, v2
	v_mov_b32_e32 v13, v2
	v_mov_b32_e32 v14, v2
	v_mov_b32_e32 v15, v2
	v_mov_b32_e32 v16, v2
	v_mov_b32_e32 v17, v2
	v_mov_b32_e32 v26, v2
	v_mov_b32_e32 v27, v2
	v_mov_b32_e32 v28, v2
	v_mov_b32_e32 v29, v2
	v_mov_b32_e32 v30, v2
	v_mov_b32_e32 v31, v2
	v_mov_b32_e32 v32, v2
	v_mov_b32_e32 v33, v2
	v_mov_b32_e32 v42, v2
	v_mov_b32_e32 v43, v2
	v_mov_b32_e32 v44, v2
	v_mov_b32_e32 v45, v2
	v_mov_b32_e32 v46, v2
	v_mov_b32_e32 v47, v2
	v_mov_b32_e32 v48, v2
	v_mov_b32_e32 v49, v2
	v_mov_b32_e32 v58, v2
	v_mov_b32_e32 v59, v2
	v_mov_b32_e32 v60, v2
	v_mov_b32_e32 v61, v2
	v_mov_b32_e32 v62, v2
	v_mov_b32_e32 v63, v2
	v_mov_b32_e32 v64, v2
	v_mov_b32_e32 v65, v2
	v_mov_b32_e32 v66, v2
	v_mov_b32_e32 v67, v2
	v_mov_b32_e32 v68, v2
	v_mov_b32_e32 v69, v2
	v_mov_b32_e32 v70, v2
	v_mov_b32_e32 v71, v2
	v_mov_b32_e32 v72, v2
	v_mov_b32_e32 v73, v2
	v_mov_b32_e32 v82, v2
	v_mov_b32_e32 v83, v2
	v_mov_b32_e32 v84, v2
	v_mov_b32_e32 v85, v2
	v_mov_b32_e32 v86, v2
	v_mov_b32_e32 v87, v2
	v_mov_b32_e32 v88, v2
	v_mov_b32_e32 v89, v2
	v_mov_b32_e32 v98, v2
	v_mov_b32_e32 v99, v2
	v_mov_b32_e32 v100, v2
	v_mov_b32_e32 v101, v2
	v_mov_b32_e32 v102, v2
	s_waitcnt vmcnt(0)
	v_mov_b32_e32 v103, v2
	v_mov_b32_e32 v104, v2
	v_mov_b32_e32 v105, v2
	v_mov_b32_e32 v114, v2
	v_mov_b32_e32 v115, v2
	v_mov_b32_e32 v116, v2
	v_mov_b32_e32 v117, v2
	v_mov_b32_e32 v118, v2
	v_mov_b32_e32 v119, v2
	v_mov_b32_e32 v120, v2
	v_mov_b32_e32 v121, v2
	v_mov_b32_e32 v74, v2
	v_mov_b32_e32 v75, v2
	v_mov_b32_e32 v76, v2
	v_mov_b32_e32 v77, v2
	v_mov_b32_e32 v78, v2
	v_mov_b32_e32 v79, v2
	v_mov_b32_e32 v80, v2
	v_mov_b32_e32 v81, v2
	v_mov_b32_e32 v90, v2
	v_mov_b32_e32 v91, v2
	v_mov_b32_e32 v92, v2
	v_mov_b32_e32 v93, v2
	v_mov_b32_e32 v94, v2
	v_mov_b32_e32 v95, v2
	v_mov_b32_e32 v96, v2
	v_mov_b32_e32 v97, v2
	v_mov_b32_e32 v106, v2
	v_mov_b32_e32 v107, v2
	v_mov_b32_e32 v108, v2
	v_mov_b32_e32 v109, v2
	v_mov_b32_e32 v110, v2
	v_mov_b32_e32 v111, v2
	v_mov_b32_e32 v112, v2
	v_mov_b32_e32 v113, v2
	v_mov_b32_e32 v122, v2
	v_mov_b32_e32 v123, v2
	v_mov_b32_e32 v124, v2
	v_mov_b32_e32 v125, v2
	v_mov_b32_e32 v126, v2
	v_mov_b32_e32 v127, v2
	v_mov_b32_e32 v128, v2
	v_mov_b32_e32 v129, v2
	v_readlane_b32 s61, v254, 46
	v_readlane_b32 s62, v254, 47
	v_readlane_b32 s63, v254, 48
	v_readlane_b32 s64, v254, 49
	v_readlane_b32 s65, v254, 50
	v_readlane_b32 s66, v254, 51
	v_readlane_b32 s67, v254, 52
	v_readlane_b32 s68, v254, 53
	v_readlane_b32 s69, v254, 54
	v_readlane_b32 s70, v254, 55
	v_readlane_b32 s71, v254, 56
	v_readlane_b32 s72, v254, 57
	v_readlane_b32 s73, v254, 58
	.p2align	6

; template <int kind>
; __device__ void attn_job(const Params& p, int layer, int idx, char* smem) {
;     ...
;     b = idx >> 5; const int kvh = (idx >> 4) & 1, qt = idx & 15;
;     const int head = kvh * 2 + (w >> 2);
;     qtok = b * SEQ + qt * 128 + (w & 3) * 32 + tq; qcol = GQ + head * 64; ocol = 512 + head * 64;
;     kcol = GK + kvh * 64; vcol = GV + kvh * 64; nlat = 32; lat0 = b * SEQ;
;     ...
;   bf16x8 qf[4];
; #pragma unroll
;   for (int st = 0; st < 4; ++st) qf[st] = *(const bf16x8*)(Z + (size_t)qtok * ZW + qcol + 16 * st + 8 * hh);
;   unsigned colmask = 0;
;   int dcbase = 0;
;   if (kind == 1) {
;     const int cs = min(max(qc - 8, 0), 48);
; #pragma unroll
;     for (int e = 0; e < 16; ++e) {
;       const int kc = k0 + (e & 3) + 8 * (e >> 2) + 4 * hh;
;       colmask |= ((kc >= cs) && (kc < cs + 16)) ? (1u << e) : 0u;
;     }
;     dcbase = 16 + k0 + 4 * hh - qc + 15;
;   }
;   float mrun = -1e30f, lsum = 0.f;
;   f32x16 O[2], zero16;
; #pragma unroll
;   for (int i = 0; i < 16; ++i) { O[0][i] = 0.f; O[1][i] = 0.f; zero16[i] = 0.f; }
;   asm volatile("" : "+v"(zero16));
;   const int lkey = tid >> 3, lc = tid & 7;
;   const unsigned vlane_off = (unsigned)((4 * (lane >> 5) + ((lane & 15) >> 2)) * (KS_STRIDE * 2) + (((lane >> 4) & 1) * 16 + 4 * (lane & 3)) * 2);
;   auto tile_row0 = [&](int i) { return (i < 4) ? (NLAT + b * CTXL + i * 64) : (lat0 + (i - 4) * 64); };
;   u32x4 kreg, vreg;
;   {
;     const size_t ro = (size_t)(tile_row0(0) + lkey) * ZW;
;     kreg = *(const u32x4*)(Z + ro + kcol + lc * 8);
;     vreg = *(const u32x4*)(Z + ro + vcol + lc * 8);
;   }
.Lprio_skip_gqa:
	s_add_i32 s0, s18, 0xffffff00
	s_lshr_b32 s1, s0, 5
	s_bfe_u32 s2, s18, 0x10004
	v_mov_b32_e32 v22, v234
	s_lshl_b32 s4, s1, 11
	s_lshl_b32 s3, s2, 6
	s_lshl_b32 s5, s1, 8
	s_lshl_b32 s1, s2, 7
	s_lshl_b32 s0, s0, 7
	v_readfirstlane_b32 s2, v22
	s_lshr_b32 s6, s2, 1
	s_and_b32 s0, s0, 0x780
	s_and_b32 s6, s6, 0x60
	s_or_b32 s0, s0, s6
	v_and_b32_e32 v23, 31, v22
	s_or_b32 s0, s0, s4
	s_waitcnt vmcnt(5)
	v_or_b32_e32 v139, s0, v23
	s_ashr_i32 s0, s2, 2
	s_andn2_b32 s0, s0, 63
	s_add_i32 s0, s0, s1
	s_movk_i32 s1, 0xe00
	v_mul_lo_u32 v0, v139, s1
	v_bfe_u32 v24, v22, 5, 1
	v_lshl_add_u64 v[2:3], v[0:1], 1, s[80:81]
	s_ashr_i32 s1, s0, 31
	s_or_b32 s7, s3, 0xa00
	s_or_b32 s8, s3, 0xa80
	s_add_i32 s3, s5, 0x8000
	v_lshl_add_u64 v[2:3], s[0:1], 1, v[2:3]
	s_waitcnt vmcnt(4)
	v_lshlrev_b32_e32 v140, 4, v24
	v_mov_b32_e32 v141, v1
	v_ashrrev_i32_e32 v25, 3, v22
	v_mov_b64_e32 v[16:17], s[80:81]
	v_lshl_add_u64 v[2:3], v[2:3], 0, v[140:141]
	s_mov_b64 s[10:11], 0x1200
	s_movk_i32 s2, 0x1000
	v_add_u32_e32 v18, s3, v25
	v_lshl_add_u64 v[4:5], v[2:3], 0, s[10:11]
	v_add_co_u32_e32 v2, vcc, s2, v2
	v_mad_i64_i32 v[16:17], s[2:3], v18, s79, v[16:17]
	v_readlane_b32 s2, v254, 34
	v_lshlrev_b32_e32 v20, 3, v22
	v_addc_co_u32_e32 v3, vcc, 0, v3, vcc
	v_mov_b32_e32 v14, v1
	v_mov_b32_e32 v15, v1
	v_readlane_b32 s3, v254, 35
	s_lshl_b32 s2, s7, 1
	v_and_b32_e32 v142, 56, v20
	global_load_dwordx4 v[90:93], v[4:5], off offset:32
	global_load_dwordx4 v[86:89], v[4:5], off offset:64
	global_load_dwordx4 v[94:97], v[2:3], off offset:512
	global_load_dwordx4 v[82:85], v[4:5], off offset:96
	v_mov_b32_e32 v0, v1
	v_mov_b32_e32 v2, v1
	v_mov_b32_e32 v3, v1
	v_mov_b32_e32 v4, v1
	v_mov_b32_e32 v5, v1
	v_mov_b32_e32 v6, v1
	v_mov_b32_e32 v7, v1
	v_mov_b32_e32 v8, v1
	v_mov_b32_e32 v9, v1
	v_mov_b32_e32 v10, v1
	v_mov_b32_e32 v11, v1
	v_mov_b32_e32 v12, v1
	v_mov_b32_e32 v13, v1
	v_mov_b64_e32 v[48:49], v[14:15]
	v_lshl_add_u64 v[18:19], v[16:17], 0, s[2:3]
	v_lshlrev_b32_e32 v20, 1, v142
	v_mov_b32_e32 v21, v1
	s_lshl_b32 s2, s8, 1
	v_mov_b64_e32 v[46:47], v[12:13]
	v_mov_b64_e32 v[44:45], v[10:11]
	v_mov_b64_e32 v[42:43], v[8:9]
	v_mov_b64_e32 v[40:41], v[6:7]
	v_mov_b64_e32 v[38:39], v[4:5]
	v_mov_b64_e32 v[36:37], v[2:3]
	v_mov_b64_e32 v[34:35], v[0:1]
	v_lshl_add_u64 v[18:19], v[18:19], 0, v[20:21]
	v_lshl_add_u64 v[16:17], v[16:17], 0, s[2:3]
	v_lshl_add_u64 v[16:17], v[16:17], 0, v[20:21]
	global_load_dwordx4 v[98:101], v[18:19], off
	global_load_dwordx4 v[102:105], v[16:17], off
	v_and_b32_e32 v17, 16, v22
	v_lshlrev_b32_e32 v18, 2, v22
	v_bfe_u32 v16, v22, 2, 2
	v_and_or_b32 v17, v18, 12, v17
	v_lshl_or_b32 v16, v24, 2, v16
	v_lshlrev_b32_e32 v17, 1, v17
	s_movk_i32 s2, 0x90
	v_mad_u32_u24 v141, v16, s2, v17
	s_movk_i32 s2, 0x48
	v_lshlrev_b32_e32 v138, 3, v24
	v_mul_lo_u32 v16, v25, s2
	v_mul_u32_u24_e32 v143, 0x90, v23
	v_add_u32_e32 v147, 64, v25
	s_lshl_b32 s2, s7, 1
	v_mov_b64_e32 v[32:33], v[14:15]
	v_writelane_b32 v254, s2, 34
	v_lshlrev_b32_e32 v148, 1, v16
	v_mov_b64_e32 v[30:31], v[12:13]
	v_mov_b64_e32 v[28:29], v[10:11]
	v_mov_b64_e32 v[26:27], v[8:9]
	v_mov_b64_e32 v[24:25], v[6:7]
	v_mov_b64_e32 v[22:23], v[4:5]
	v_mov_b64_e32 v[20:21], v[2:3]
	v_mov_b64_e32 v[18:19], v[0:1]
	v_mov_b64_e32 v[16:17], v[14:15]
	s_mov_b32 s6, 0
	v_mov_b32_e32 v149, 0
	v_mov_b32_e32 v145, 0xf149f2ca
	v_writelane_b32 v254, s3, 35
	s_lshl_b32 s2, s8, 1
	s_mov_b32 s7, 0
	v_mov_b64_e32 v[14:15], v[12:13]
	v_mov_b64_e32 v[12:13], v[10:11]
	v_mov_b64_e32 v[10:11], v[8:9]
	v_mov_b64_e32 v[8:9], v[6:7]
	v_mov_b64_e32 v[6:7], v[4:5]
	v_mov_b64_e32 v[4:5], v[2:3]
	v_mov_b64_e32 v[2:3], v[0:1]
	.p2align	6

; DI int opaque_tid() { int t = threadIdx.x; asm volatile("" : "+v"(t)); return t; }
; #define WAIT_V(n) asm volatile("s_waitcnt vmcnt(" #n ")" ::: "memory")
; #define WAIT_L(n) asm volatile("s_waitcnt lgkmcnt(" #n ")" ::: "memory")
; #define BAR __builtin_amdgcn_s_barrier()
; #define SCHED __builtin_amdgcn_sched_barrier(0)
;     ...
;     const bool has_next = unit(ui + 1, npm, npn, nkq);
;     const char* nA = has_next ? (const char*)A + (size_t)npm * tstep + (nkq > 0 ? (size_t)nkq * (K / 4) * 2 : 0) : cA;
;     const char* nB = has_next ? (const char*)Bt + (size_t)npn * tstep + (nkq > 0 ? (size_t)nkq * (K / 4) * 2 : 0) : cB;
;     const int ntu = (SPLIT && kq >= 0) ? nt / 4 : nt;
;     for (int t = 0; t < ntu; t += 2) {
;       const bool last = (t == ntu - 2);
;       const char* a1 = cA + (size_t)(t + 1) * kstep;
;       const char* a2 = last ? nA : cA + (size_t)(t + 2) * kstep;
;       const char* b2 = last ? nB : cB + (size_t)(t + 2) * kstep;
;       const char* a3 = a2 + kstep;
;       const char* b3 = b2 + kstep;
;       LDB(B0, 0, 0); LDB(B1, 0, 1); SCHED; LDA(At, 0, 0); STAGE(SAo(1, 1), a1 + hstep, voff);
;       WAIT_V(8); WAIT_L(0); BAR; MMA(0, 0, At, B0); MMA(0, 1, At, B1); BAR; SCHED;
;       LDA(At, 0, 1); STAGE(SBo(0, 0), b2, voffB); STAGE(SBo(0, 1), b2 + hstep, voffB); STAGE(SAo(0, 0), a2, voff);
;       WAIT_V(8); WAIT_L(0); BAR; MMA(1, 0, At, B0); MMA(1, 1, At, B1); BAR; SCHED;
;       LDB(B0, 1, 0); LDB(B1, 1, 1); SCHED; LDA(At, 1, 0); STAGE(SAo(0, 1), a2 + hstep, voff);
;       WAIT_V(8); WAIT_L(0); BAR; MMA(0, 0, At, B0); MMA(0, 1, At, B1); BAR; SCHED;
;       LDA(At, 1, 1); STAGE(SBo(1, 0), b3, voffB); STAGE(SBo(1, 1), b3 + hstep, voffB); STAGE(SAo(1, 0), a3, voff);
;       WAIT_V(8); WAIT_L(0); BAR; MMA(1, 0, At, B0); MMA(1, 1, At, B1); BAR; SCHED;
;     }
;     if (wr == 0) BAR;
;     {
;       const int tid2 = opaque_tid(), lane2 = tid2 & 63;
;       gemm_epilogue<EPI>(p, layer, acc, pm * BM, pn * BM, pn, wr, wc, lane2 & 15, lane2 >> 4, (char*)shm + XCH_OFF, SPLIT ? kq : -1);
;     }
;     if (!has_next) break;
; #pragma unroll
;     for (int a = 0; a < 2; ++a)
; #pragma unroll
;       for (int b = 0; b < 2; ++b)
; #pragma unroll
;         for (int m = 0; m < 4; ++m)
; #pragma unroll
;           for (int n = 0; n < 2; ++n) acc[a][b][m][n] = (f32x4){0.f, 0.f, 0.f, 0.f};
.LBB0_905:
	s_nop 0
	v_readlane_b32 s10, v254, 34
	v_readlane_b32 s11, v254, 35
	v_readlane_b32 s60, v254, 45
	s_lshl_b64 s[10:11], s[10:11], 19
	v_readlane_b32 s74, v254, 59
	v_readlane_b32 s75, v254, 60
	s_add_u32 s10, s74, s10
	s_addc_u32 s11, s75, s11
	s_and_b64 s[12:13], s[0:1], exec
	s_cselect_b32 s17, s11, s15
	s_cselect_b32 s19, s10, s14
	s_ashr_i32 s9, s8, 31
	s_lshl_b64 s[12:13], s[8:9], 19
	s_add_u32 s12, s24, s12
	s_addc_u32 s13, s25, s13
	s_and_b64 s[22:23], s[0:1], exec
	s_cselect_b32 s9, s13, s21
	s_cselect_b32 s49, s12, s20
	s_add_u32 s14, s14, 0x40080
	s_addc_u32 s15, s15, 0
	s_add_u32 s50, s20, 0x100
	v_mov_b32_e32 v2, 0
	s_addc_u32 s51, s21, 0
	s_mov_b32 s52, -2
	v_mov_b32_e32 v3, v2
	v_mov_b32_e32 v4, v2
	v_mov_b32_e32 v5, v2
	v_mov_b32_e32 v6, v2
	v_mov_b32_e32 v7, v2
	v_mov_b32_e32 v8, v2
	v_mov_b32_e32 v9, v2
	v_mov_b32_e32 v18, v2
	v_mov_b32_e32 v19, v2
	v_mov_b32_e32 v20, v2
	v_mov_b32_e32 v21, v2
	v_mov_b32_e32 v22, v2
	v_mov_b32_e32 v23, v2
	v_mov_b32_e32 v24, v2
	v_mov_b32_e32 v25, v2
	v_mov_b32_e32 v34, v2
	v_mov_b32_e32 v35, v2
	v_mov_b32_e32 v36, v2
	v_mov_b32_e32 v37, v2
	v_mov_b32_e32 v38, v2
	v_mov_b32_e32 v39, v2
	v_mov_b32_e32 v40, v2
	v_mov_b32_e32 v41, v2
	v_mov_b32_e32 v50, v2
	v_mov_b32_e32 v51, v2
	v_mov_b32_e32 v52, v2
	v_mov_b32_e32 v53, v2
	v_mov_b32_e32 v54, v2
	v_mov_b32_e32 v55, v2
	v_mov_b32_e32 v56, v2
	v_mov_b32_e32 v57, v2
	v_mov_b32_e32 v10, v2
	v_mov_b32_e32 v11, v2
	v_mov_b32_e32 v12, v2
	v_mov_b32_e32 v13, v2
	v_mov_b32_e32 v14, v2
	v_mov_b32_e32 v15, v2
	v_mov_b32_e32 v16, v2
	v_mov_b32_e32 v17, v2
	v_mov_b32_e32 v26, v2
	v_mov_b32_e32 v27, v2
	v_mov_b32_e32 v28, v2
	v_mov_b32_e32 v29, v2
	v_mov_b32_e32 v30, v2
	v_mov_b32_e32 v31, v2
	v_mov_b32_e32 v32, v2
	v_mov_b32_e32 v33, v2
	v_mov_b32_e32 v42, v2
	v_mov_b32_e32 v43, v2
	v_mov_b32_e32 v44, v2
	v_mov_b32_e32 v45, v2
	v_mov_b32_e32 v46, v2
	v_mov_b32_e32 v47, v2
	v_mov_b32_e32 v48, v2
	v_mov_b32_e32 v49, v2
	v_mov_b32_e32 v58, v2
	v_mov_b32_e32 v59, v2
	v_mov_b32_e32 v60, v2
	v_mov_b32_e32 v61, v2
	v_mov_b32_e32 v62, v2
	v_mov_b32_e32 v63, v2
	v_mov_b32_e32 v64, v2
	v_mov_b32_e32 v65, v2
	v_mov_b32_e32 v66, v2
	v_mov_b32_e32 v67, v2
	v_mov_b32_e32 v68, v2
	v_mov_b32_e32 v69, v2
	v_mov_b32_e32 v70, v2
	v_mov_b32_e32 v71, v2
	v_mov_b32_e32 v72, v2
	v_mov_b32_e32 v73, v2
	v_mov_b32_e32 v82, v2
	v_mov_b32_e32 v83, v2
	v_mov_b32_e32 v84, v2
	v_mov_b32_e32 v85, v2
	v_mov_b32_e32 v86, v2
	v_mov_b32_e32 v87, v2
	v_mov_b32_e32 v88, v2
	v_mov_b32_e32 v89, v2
	s_waitcnt vmcnt(0)
	v_mov_b32_e32 v98, v2
	v_mov_b32_e32 v99, v2
	v_mov_b32_e32 v100, v2
	v_mov_b32_e32 v101, v2
	v_mov_b32_e32 v102, v2
	v_mov_b32_e32 v103, v2
	v_mov_b32_e32 v104, v2
	v_mov_b32_e32 v105, v2
	v_mov_b32_e32 v126, v2
	v_mov_b32_e32 v127, v2
	v_mov_b32_e32 v128, v2
	v_mov_b32_e32 v129, v2
	v_mov_b32_e32 v134, v2
	v_mov_b32_e32 v135, v2
	v_mov_b32_e32 v136, v2
	v_mov_b32_e32 v137, v2
	v_mov_b32_e32 v74, v2
	v_mov_b32_e32 v75, v2
	v_mov_b32_e32 v76, v2
	v_mov_b32_e32 v77, v2
	v_mov_b32_e32 v78, v2
	v_mov_b32_e32 v79, v2
	v_mov_b32_e32 v80, v2
	v_mov_b32_e32 v81, v2
	v_mov_b32_e32 v90, v2
	v_mov_b32_e32 v91, v2
	v_mov_b32_e32 v92, v2
	v_mov_b32_e32 v93, v2
	v_mov_b32_e32 v94, v2
	v_mov_b32_e32 v95, v2
	v_mov_b32_e32 v96, v2
	v_mov_b32_e32 v97, v2
	v_mov_b32_e32 v110, v2
	v_mov_b32_e32 v111, v2
	v_mov_b32_e32 v112, v2
	v_mov_b32_e32 v113, v2
	v_mov_b32_e32 v122, v2
	v_mov_b32_e32 v123, v2
	v_mov_b32_e32 v124, v2
	v_mov_b32_e32 v125, v2
	v_mov_b32_e32 v138, v2
	v_mov_b32_e32 v139, v2
	v_mov_b32_e32 v140, v2
	v_mov_b32_e32 v141, v2
	v_mov_b32_e32 v142, v2
	v_mov_b32_e32 v143, v2
	v_mov_b32_e32 v144, v2
	v_mov_b32_e32 v145, v2
	v_readlane_b32 s61, v254, 46
	v_readlane_b32 s62, v254, 47
	v_readlane_b32 s63, v254, 48
	v_readlane_b32 s64, v254, 49
	v_readlane_b32 s65, v254, 50
	v_readlane_b32 s66, v254, 51
	v_readlane_b32 s67, v254, 52
	v_readlane_b32 s68, v254, 53
	v_readlane_b32 s69, v254, 54
	v_readlane_b32 s70, v254, 55
	v_readlane_b32 s71, v254, 56
	v_readlane_b32 s72, v254, 57
	v_readlane_b32 s73, v254, 58
	.p2align	6

; DI int opaque_tid() { int t = threadIdx.x; asm volatile("" : "+v"(t)); return t; }
; #define WAIT_V(n) asm volatile("s_waitcnt vmcnt(" #n ")" ::: "memory")
; #define WAIT_L(n) asm volatile("s_waitcnt lgkmcnt(" #n ")" ::: "memory")
; #define BAR __builtin_amdgcn_s_barrier()
; #define SCHED __builtin_amdgcn_sched_barrier(0)
;     ...
;     const bool has_next = unit(ui + 1, npm, npn, nkq);
;     const char* nA = has_next ? (const char*)A + (size_t)npm * tstep + (nkq > 0 ? (size_t)nkq * (K / 4) * 2 : 0) : cA;
;     const char* nB = has_next ? (const char*)Bt + (size_t)npn * tstep + (nkq > 0 ? (size_t)nkq * (K / 4) * 2 : 0) : cB;
;     const int ntu = (SPLIT && kq >= 0) ? nt / 4 : nt;
;     for (int t = 0; t < ntu; t += 2) {
;       const bool last = (t == ntu - 2);
;       const char* a1 = cA + (size_t)(t + 1) * kstep;
;       const char* a2 = last ? nA : cA + (size_t)(t + 2) * kstep;
;       const char* b2 = last ? nB : cB + (size_t)(t + 2) * kstep;
;       const char* a3 = a2 + kstep;
;       const char* b3 = b2 + kstep;
;       LDB(B0, 0, 0); LDB(B1, 0, 1); SCHED; LDA(At, 0, 0); STAGE(SAo(1, 1), a1 + hstep, voff);
;       WAIT_V(8); WAIT_L(0); BAR; MMA(0, 0, At, B0); MMA(0, 1, At, B1); BAR; SCHED;
;       LDA(At, 0, 1); STAGE(SBo(0, 0), b2, voffB); STAGE(SBo(0, 1), b2 + hstep, voffB); STAGE(SAo(0, 0), a2, voff);
;       WAIT_V(8); WAIT_L(0); BAR; MMA(1, 0, At, B0); MMA(1, 1, At, B1); BAR; SCHED;
;       LDB(B0, 1, 0); LDB(B1, 1, 1); SCHED; LDA(At, 1, 0); STAGE(SAo(0, 1), a2 + hstep, voff);
;       WAIT_V(8); WAIT_L(0); BAR; MMA(0, 0, At, B0); MMA(0, 1, At, B1); BAR; SCHED;
;       LDA(At, 1, 1); STAGE(SBo(1, 0), b3, voffB); STAGE(SBo(1, 1), b3 + hstep, voffB); STAGE(SAo(1, 0), a3, voff);
;       WAIT_V(8); WAIT_L(0); BAR; MMA(1, 0, At, B0); MMA(1, 1, At, B1); BAR; SCHED;
;     }
;     if (wr == 0) BAR;
;     {
;       const int tid2 = opaque_tid(), lane2 = tid2 & 63;
;       gemm_epilogue<EPI>(p, layer, acc, pm * BM, pn * BM, pn, wr, wc, lane2 & 15, lane2 >> 4, (char*)shm + XCH_OFF, SPLIT ? kq : -1);
;     }
;     if (!has_next) break;
; #pragma unroll
;     for (int a = 0; a < 2; ++a)
; #pragma unroll
;       for (int b = 0; b < 2; ++b)
; #pragma unroll
;         for (int m = 0; m < 4; ++m)
; #pragma unroll
;           for (int n = 0; n < 2; ++n) acc[a][b][m][n] = (f32x4){0.f, 0.f, 0.f, 0.f};
.LBB0_993:
	s_ashr_i32 s11, s10, 31
	s_lshl_b64 s[14:15], s[10:11], 19
	s_add_u32 s14, s76, s14
	s_addc_u32 s15, s77, s15
	s_and_b64 s[16:17], s[0:1], exec
	s_cselect_b32 s11, s15, s21
	s_cselect_b32 s48, s14, s20
	s_ashr_i32 s13, s12, 31
	s_lshl_b64 s[16:17], s[12:13], 19
	s_add_u32 s16, s26, s16
	s_addc_u32 s17, s27, s17
	s_and_b64 s[24:25], s[0:1], exec
	s_cselect_b32 s13, s17, s23
	s_cselect_b32 s49, s16, s22
	s_add_u32 s20, s20, 0x40080
	s_addc_u32 s21, s21, 0
	s_add_u32 s50, s22, 0x100
	v_mov_b32_e32 v2, 0
	s_addc_u32 s51, s23, 0
	s_mov_b32 s52, -2
	v_mov_b32_e32 v3, v2
	v_mov_b32_e32 v4, v2
	v_mov_b32_e32 v5, v2
	v_mov_b32_e32 v6, v2
	v_mov_b32_e32 v7, v2
	v_mov_b32_e32 v8, v2
	v_mov_b32_e32 v9, v2
	v_mov_b32_e32 v18, v2
	v_mov_b32_e32 v19, v2
	v_mov_b32_e32 v20, v2
	v_mov_b32_e32 v21, v2
	v_mov_b32_e32 v22, v2
	v_mov_b32_e32 v23, v2
	v_mov_b32_e32 v24, v2
	v_mov_b32_e32 v25, v2
	v_mov_b32_e32 v34, v2
	v_mov_b32_e32 v35, v2
	v_mov_b32_e32 v36, v2
	v_mov_b32_e32 v37, v2
	v_mov_b32_e32 v38, v2
	v_mov_b32_e32 v39, v2
	v_mov_b32_e32 v40, v2
	v_mov_b32_e32 v41, v2
	v_mov_b32_e32 v50, v2
	v_mov_b32_e32 v51, v2
	v_mov_b32_e32 v52, v2
	v_mov_b32_e32 v53, v2
	v_mov_b32_e32 v54, v2
	v_mov_b32_e32 v55, v2
	v_mov_b32_e32 v56, v2
	v_mov_b32_e32 v57, v2
	v_mov_b32_e32 v10, v2
	v_mov_b32_e32 v11, v2
	v_mov_b32_e32 v12, v2
	v_mov_b32_e32 v13, v2
	v_mov_b32_e32 v14, v2
	v_mov_b32_e32 v15, v2
	v_mov_b32_e32 v16, v2
	v_mov_b32_e32 v17, v2
	v_mov_b32_e32 v26, v2
	v_mov_b32_e32 v27, v2
	v_mov_b32_e32 v28, v2
	v_mov_b32_e32 v29, v2
	v_mov_b32_e32 v30, v2
	v_mov_b32_e32 v31, v2
	v_mov_b32_e32 v32, v2
	v_mov_b32_e32 v33, v2
	v_mov_b32_e32 v42, v2
	v_mov_b32_e32 v43, v2
	v_mov_b32_e32 v44, v2
	v_mov_b32_e32 v45, v2
	v_mov_b32_e32 v46, v2
	v_mov_b32_e32 v47, v2
	v_mov_b32_e32 v48, v2
	v_mov_b32_e32 v49, v2
	v_mov_b32_e32 v58, v2
	v_mov_b32_e32 v59, v2
	v_mov_b32_e32 v60, v2
	v_mov_b32_e32 v61, v2
	v_mov_b32_e32 v62, v2
	v_mov_b32_e32 v63, v2
	v_mov_b32_e32 v64, v2
	v_mov_b32_e32 v65, v2
	v_mov_b32_e32 v66, v2
	v_mov_b32_e32 v67, v2
	v_mov_b32_e32 v68, v2
	v_mov_b32_e32 v69, v2
	v_mov_b32_e32 v70, v2
	v_mov_b32_e32 v71, v2
	v_mov_b32_e32 v72, v2
	v_mov_b32_e32 v73, v2
	v_mov_b32_e32 v82, v2
	v_mov_b32_e32 v83, v2
	v_mov_b32_e32 v84, v2
	v_mov_b32_e32 v85, v2
	v_mov_b32_e32 v86, v2
	v_mov_b32_e32 v87, v2
	v_mov_b32_e32 v88, v2
	v_mov_b32_e32 v89, v2
	v_mov_b32_e32 v98, v2
	v_mov_b32_e32 v99, v2
	v_mov_b32_e32 v100, v2
	v_mov_b32_e32 v101, v2
	v_mov_b32_e32 v102, v2
	s_waitcnt vmcnt(0)
	v_mov_b32_e32 v103, v2
	v_mov_b32_e32 v104, v2
	v_mov_b32_e32 v105, v2
	v_mov_b32_e32 v114, v2
	v_mov_b32_e32 v115, v2
	v_mov_b32_e32 v116, v2
	v_mov_b32_e32 v117, v2
	v_mov_b32_e32 v118, v2
	v_mov_b32_e32 v119, v2
	v_mov_b32_e32 v120, v2
	v_mov_b32_e32 v121, v2
	v_mov_b32_e32 v74, v2
	v_mov_b32_e32 v75, v2
	v_mov_b32_e32 v76, v2
	v_mov_b32_e32 v77, v2
	v_mov_b32_e32 v78, v2
	v_mov_b32_e32 v79, v2
	v_mov_b32_e32 v80, v2
	v_mov_b32_e32 v81, v2
	v_mov_b32_e32 v90, v2
	v_mov_b32_e32 v91, v2
	v_mov_b32_e32 v92, v2
	v_mov_b32_e32 v93, v2
	v_mov_b32_e32 v94, v2
	v_mov_b32_e32 v95, v2
	v_mov_b32_e32 v96, v2
	v_mov_b32_e32 v97, v2
	v_mov_b32_e32 v106, v2
	v_mov_b32_e32 v107, v2
	v_mov_b32_e32 v108, v2
	v_mov_b32_e32 v109, v2
	v_mov_b32_e32 v110, v2
	v_mov_b32_e32 v111, v2
	v_mov_b32_e32 v112, v2
	v_mov_b32_e32 v113, v2
	v_mov_b32_e32 v122, v2
	v_mov_b32_e32 v123, v2
	v_mov_b32_e32 v124, v2
	v_mov_b32_e32 v125, v2
	v_mov_b32_e32 v126, v2
	v_mov_b32_e32 v127, v2
	v_mov_b32_e32 v128, v2
	v_mov_b32_e32 v129, v2
	.p2align	6

; DI int opaque_tid() { int t = threadIdx.x; asm volatile("" : "+v"(t)); return t; }
; #define WAIT_V(n) asm volatile("s_waitcnt vmcnt(" #n ")" ::: "memory")
; #define WAIT_L(n) asm volatile("s_waitcnt lgkmcnt(" #n ")" ::: "memory")
; #define BAR __builtin_amdgcn_s_barrier()
; #define SCHED __builtin_amdgcn_sched_barrier(0)
;     ...
;     const bool has_next = unit(ui + 1, npm, npn, nkq);
;     const char* nA = has_next ? (const char*)A + (size_t)npm * tstep + (nkq > 0 ? (size_t)nkq * (K / 4) * 2 : 0) : cA;
;     const char* nB = has_next ? (const char*)Bt + (size_t)npn * tstep + (nkq > 0 ? (size_t)nkq * (K / 4) * 2 : 0) : cB;
;     const int ntu = (SPLIT && kq >= 0) ? nt / 4 : nt;
;     for (int t = 0; t < ntu; t += 2) {
;       const bool last = (t == ntu - 2);
;       const char* a1 = cA + (size_t)(t + 1) * kstep;
;       const char* a2 = last ? nA : cA + (size_t)(t + 2) * kstep;
;       const char* b2 = last ? nB : cB + (size_t)(t + 2) * kstep;
;       const char* a3 = a2 + kstep;
;       const char* b3 = b2 + kstep;
;       LDB(B0, 0, 0); LDB(B1, 0, 1); SCHED; LDA(At, 0, 0); STAGE(SAo(1, 1), a1 + hstep, voff);
;       WAIT_V(8); WAIT_L(0); BAR; MMA(0, 0, At, B0); MMA(0, 1, At, B1); BAR; SCHED;
;       LDA(At, 0, 1); STAGE(SBo(0, 0), b2, voffB); STAGE(SBo(0, 1), b2 + hstep, voffB); STAGE(SAo(0, 0), a2, voff);
;       WAIT_V(8); WAIT_L(0); BAR; MMA(1, 0, At, B0); MMA(1, 1, At, B1); BAR; SCHED;
;       LDB(B0, 1, 0); LDB(B1, 1, 1); SCHED; LDA(At, 1, 0); STAGE(SAo(0, 1), a2 + hstep, voff);
;       WAIT_V(8); WAIT_L(0); BAR; MMA(0, 0, At, B0); MMA(0, 1, At, B1); BAR; SCHED;
;       LDA(At, 1, 1); STAGE(SBo(1, 0), b3, voffB); STAGE(SBo(1, 1), b3 + hstep, voffB); STAGE(SAo(1, 0), a3, voff);
;       WAIT_V(8); WAIT_L(0); BAR; MMA(1, 0, At, B0); MMA(1, 1, At, B1); BAR; SCHED;
;     }
;     if (wr == 0) BAR;
;     {
;       const int tid2 = opaque_tid(), lane2 = tid2 & 63;
;       gemm_epilogue<EPI>(p, layer, acc, pm * BM, pn * BM, pn, wr, wc, lane2 & 15, lane2 >> 4, (char*)shm + XCH_OFF, SPLIT ? kq : -1);
;     }
;     if (!has_next) break;
; #pragma unroll
;     for (int a = 0; a < 2; ++a)
; #pragma unroll
;       for (int b = 0; b < 2; ++b)
; #pragma unroll
;         for (int m = 0; m < 4; ++m)
; #pragma unroll
;           for (int n = 0; n < 2; ++n) acc[a][b][m][n] = (f32x4){0.f, 0.f, 0.f, 0.f};
.LBB0_1063:
	v_readlane_b32 s8, v254, 34
	v_readlane_b32 s9, v254, 35
	s_mov_b32 s7, s9
	s_lshl_b64 s[8:9], s[6:7], 21
	s_add_u32 s8, s84, s8
	s_addc_u32 s9, s85, s9
	s_and_b64 s[10:11], s[0:1], exec
	s_cselect_b32 s7, s9, s13
	s_cselect_b32 s42, s8, s12
	s_lshl_b32 s10, s31, 21
	s_add_u32 s10, s24, s10
	s_addc_u32 s11, s25, 0
	s_and_b64 s[16:17], s[0:1], exec
	s_cselect_b32 s43, s11, s15
	s_cselect_b32 s44, s10, s14
	s_add_u32 s12, s12, 0x100080
	s_addc_u32 s13, s13, 0
	s_add_u32 s45, s14, 0x100
	v_mov_b32_e32 v2, 0
	s_addc_u32 s46, s15, 0
	s_mov_b32 s47, -2
	v_mov_b32_e32 v3, v2
	v_mov_b32_e32 v4, v2
	v_mov_b32_e32 v5, v2
	v_mov_b32_e32 v6, v2
	v_mov_b32_e32 v7, v2
	v_mov_b32_e32 v8, v2
	v_mov_b32_e32 v9, v2
	v_mov_b32_e32 v10, v2
	v_mov_b32_e32 v11, v2
	v_mov_b32_e32 v12, v2
	v_mov_b32_e32 v13, v2
	v_mov_b32_e32 v18, v2
	v_mov_b32_e32 v19, v2
	v_mov_b32_e32 v20, v2
	v_mov_b32_e32 v21, v2
	v_mov_b32_e32 v30, v2
	v_mov_b32_e32 v31, v2
	v_mov_b32_e32 v32, v2
	v_mov_b32_e32 v33, v2
	v_mov_b32_e32 v38, v2
	v_mov_b32_e32 v39, v2
	v_mov_b32_e32 v40, v2
	v_mov_b32_e32 v41, v2
	v_mov_b32_e32 v42, v2
	v_mov_b32_e32 v43, v2
	v_mov_b32_e32 v44, v2
	v_mov_b32_e32 v45, v2
	v_mov_b32_e32 v50, v2
	v_mov_b32_e32 v51, v2
	v_mov_b32_e32 v52, v2
	v_mov_b32_e32 v53, v2
	v_mov_b32_e32 v14, v2
	v_mov_b32_e32 v15, v2
	v_mov_b32_e32 v16, v2
	v_mov_b32_e32 v17, v2
	v_mov_b32_e32 v22, v2
	v_mov_b32_e32 v23, v2
	v_mov_b32_e32 v24, v2
	v_mov_b32_e32 v25, v2
	v_mov_b32_e32 v26, v2
	v_mov_b32_e32 v27, v2
	v_mov_b32_e32 v28, v2
	v_mov_b32_e32 v29, v2
	v_mov_b32_e32 v34, v2
	v_mov_b32_e32 v35, v2
	v_mov_b32_e32 v36, v2
	v_mov_b32_e32 v37, v2
	v_mov_b32_e32 v46, v2
	v_mov_b32_e32 v47, v2
	v_mov_b32_e32 v48, v2
	v_mov_b32_e32 v49, v2
	v_mov_b32_e32 v54, v2
	v_mov_b32_e32 v55, v2
	v_mov_b32_e32 v56, v2
	v_mov_b32_e32 v57, v2
	v_mov_b32_e32 v58, v2
	v_mov_b32_e32 v59, v2
	v_mov_b32_e32 v60, v2
	v_mov_b32_e32 v61, v2
	v_mov_b32_e32 v62, v2
	v_mov_b32_e32 v63, v2
	v_mov_b32_e32 v64, v2
	v_mov_b32_e32 v65, v2
	v_mov_b32_e32 v66, v2
	v_mov_b32_e32 v67, v2
	v_mov_b32_e32 v68, v2
	v_mov_b32_e32 v69, v2
	v_mov_b32_e32 v70, v2
	v_mov_b32_e32 v71, v2
	v_mov_b32_e32 v72, v2
	v_mov_b32_e32 v73, v2
	v_mov_b32_e32 v74, v2
	v_mov_b32_e32 v75, v2
	v_mov_b32_e32 v76, v2
	v_mov_b32_e32 v77, v2
	v_mov_b32_e32 v82, v2
	v_mov_b32_e32 v83, v2
	v_mov_b32_e32 v84, v2
	v_mov_b32_e32 v85, v2
	v_mov_b32_e32 v98, v2
	v_mov_b32_e32 v99, v2
	v_mov_b32_e32 v100, v2
	v_mov_b32_e32 v101, v2
	v_mov_b32_e32 v102, v2
	s_waitcnt vmcnt(0)
	v_mov_b32_e32 v103, v2
	v_mov_b32_e32 v104, v2
	v_mov_b32_e32 v105, v2
	v_mov_b32_e32 v106, v2
	v_mov_b32_e32 v107, v2
	v_mov_b32_e32 v108, v2
	v_mov_b32_e32 v109, v2
	v_mov_b32_e32 v118, v2
	v_mov_b32_e32 v119, v2
	v_mov_b32_e32 v120, v2
	v_mov_b32_e32 v121, v2
	v_mov_b32_e32 v78, v2
	v_mov_b32_e32 v79, v2
	v_mov_b32_e32 v80, v2
	v_mov_b32_e32 v81, v2
	v_mov_b32_e32 v86, v2
	v_mov_b32_e32 v87, v2
	v_mov_b32_e32 v88, v2
	v_mov_b32_e32 v89, v2
	v_mov_b32_e32 v90, v2
	v_mov_b32_e32 v91, v2
	v_mov_b32_e32 v92, v2
	v_mov_b32_e32 v93, v2
	v_mov_b32_e32 v94, v2
	v_mov_b32_e32 v95, v2
	v_mov_b32_e32 v96, v2
	v_mov_b32_e32 v97, v2
	v_mov_b32_e32 v110, v2
	v_mov_b32_e32 v111, v2
	v_mov_b32_e32 v112, v2
	v_mov_b32_e32 v113, v2
	v_mov_b32_e32 v114, v2
	v_mov_b32_e32 v115, v2
	v_mov_b32_e32 v116, v2
	v_mov_b32_e32 v117, v2
	v_mov_b32_e32 v122, v2
	v_mov_b32_e32 v123, v2
	v_mov_b32_e32 v124, v2
	v_mov_b32_e32 v125, v2
	v_mov_b32_e32 v126, v2
	v_mov_b32_e32 v127, v2
	v_mov_b32_e32 v128, v2
	v_mov_b32_e32 v129, v2
	.p2align	6

; DI int opaque_tid() { int t = threadIdx.x; asm volatile("" : "+v"(t)); return t; }
; #define WAIT_V(n) asm volatile("s_waitcnt vmcnt(" #n ")" ::: "memory")
; #define WAIT_L(n) asm volatile("s_waitcnt lgkmcnt(" #n ")" ::: "memory")
; #define BAR __builtin_amdgcn_s_barrier()
; #define SCHED __builtin_amdgcn_sched_barrier(0)
;     ...
;     const bool has_next = unit(ui + 1, npm, npn, nkq);
;     const char* nA = has_next ? (const char*)A + (size_t)npm * tstep + (nkq > 0 ? (size_t)nkq * (K / 4) * 2 : 0) : cA;
;     const char* nB = has_next ? (const char*)Bt + (size_t)npn * tstep + (nkq > 0 ? (size_t)nkq * (K / 4) * 2 : 0) : cB;
;     const int ntu = (SPLIT && kq >= 0) ? nt / 4 : nt;
;     for (int t = 0; t < ntu; t += 2) {
;       const bool last = (t == ntu - 2);
;       const char* a1 = cA + (size_t)(t + 1) * kstep;
;       const char* a2 = last ? nA : cA + (size_t)(t + 2) * kstep;
;       const char* b2 = last ? nB : cB + (size_t)(t + 2) * kstep;
;       const char* a3 = a2 + kstep;
;       const char* b3 = b2 + kstep;
;       LDB(B0, 0, 0); LDB(B1, 0, 1); SCHED; LDA(At, 0, 0); STAGE(SAo(1, 1), a1 + hstep, voff);
;       WAIT_V(8); WAIT_L(0); BAR; MMA(0, 0, At, B0); MMA(0, 1, At, B1); BAR; SCHED;
;       LDA(At, 0, 1); STAGE(SBo(0, 0), b2, voffB); STAGE(SBo(0, 1), b2 + hstep, voffB); STAGE(SAo(0, 0), a2, voff);
;       WAIT_V(8); WAIT_L(0); BAR; MMA(1, 0, At, B0); MMA(1, 1, At, B1); BAR; SCHED;
;       LDB(B0, 1, 0); LDB(B1, 1, 1); SCHED; LDA(At, 1, 0); STAGE(SAo(0, 1), a2 + hstep, voff);
;       WAIT_V(8); WAIT_L(0); BAR; MMA(0, 0, At, B0); MMA(0, 1, At, B1); BAR; SCHED;
;       LDA(At, 1, 1); STAGE(SBo(1, 0), b3, voffB); STAGE(SBo(1, 1), b3 + hstep, voffB); STAGE(SAo(1, 0), a3, voff);
;       WAIT_V(8); WAIT_L(0); BAR; MMA(1, 0, At, B0); MMA(1, 1, At, B1); BAR; SCHED;
;     }
;     if (wr == 0) BAR;
;     {
;       const int tid2 = opaque_tid(), lane2 = tid2 & 63;
;       gemm_epilogue<EPI>(p, layer, acc, pm * BM, pn * BM, pn, wr, wc, lane2 & 15, lane2 >> 4, (char*)shm + XCH_OFF, SPLIT ? kq : -1);
;     }
;     if (!has_next) break;
; #pragma unroll
;     for (int a = 0; a < 2; ++a)
; #pragma unroll
;       for (int b = 0; b < 2; ++b)
; #pragma unroll
;         for (int m = 0; m < 4; ++m)
; #pragma unroll
;           for (int n = 0; n < 2; ++n) acc[a][b][m][n] = (f32x4){0.f, 0.f, 0.f, 0.f};
.LBB0_1139:
	s_nop 0
	v_readlane_b32 s10, v254, 34
	v_readlane_b32 s11, v254, 35
	s_lshl_b64 s[10:11], s[10:11], 21
	s_add_u32 s10, s84, s10
	s_addc_u32 s11, s85, s11
	s_and_b64 s[12:13], s[0:1], exec
	s_cselect_b32 s15, s11, s19
	s_cselect_b32 s17, s10, s18
	s_lshl_b32 s12, s45, 21
	s_add_u32 s12, s24, s12
	s_addc_u32 s13, s25, 0
	s_and_b64 s[22:23], s[0:1], exec
	s_cselect_b32 s36, s13, s21
	s_cselect_b32 s37, s12, s20
	s_add_u32 s18, s18, 0x100080
	s_addc_u32 s19, s19, 0
	s_add_u32 s46, s20, 0x100
	v_mov_b32_e32 v2, 0
	s_addc_u32 s47, s21, 0
	s_mov_b32 s48, -2
	v_mov_b32_e32 v3, v2
	v_mov_b32_e32 v4, v2
	v_mov_b32_e32 v5, v2
	v_mov_b32_e32 v6, v2
	v_mov_b32_e32 v7, v2
	v_mov_b32_e32 v8, v2
	v_mov_b32_e32 v9, v2
	v_mov_b32_e32 v18, v2
	v_mov_b32_e32 v19, v2
	v_mov_b32_e32 v20, v2
	v_mov_b32_e32 v21, v2
	v_mov_b32_e32 v22, v2
	v_mov_b32_e32 v23, v2
	v_mov_b32_e32 v24, v2
	v_mov_b32_e32 v25, v2
	v_mov_b32_e32 v34, v2
	v_mov_b32_e32 v35, v2
	v_mov_b32_e32 v36, v2
	v_mov_b32_e32 v37, v2
	v_mov_b32_e32 v38, v2
	v_mov_b32_e32 v39, v2
	v_mov_b32_e32 v40, v2
	v_mov_b32_e32 v41, v2
	v_mov_b32_e32 v50, v2
	v_mov_b32_e32 v51, v2
	v_mov_b32_e32 v52, v2
	v_mov_b32_e32 v53, v2
	v_mov_b32_e32 v54, v2
	v_mov_b32_e32 v55, v2
	v_mov_b32_e32 v56, v2
	v_mov_b32_e32 v57, v2
	v_mov_b32_e32 v10, v2
	v_mov_b32_e32 v11, v2
	v_mov_b32_e32 v12, v2
	v_mov_b32_e32 v13, v2
	v_mov_b32_e32 v14, v2
	v_mov_b32_e32 v15, v2
	v_mov_b32_e32 v16, v2
	v_mov_b32_e32 v17, v2
	v_mov_b32_e32 v26, v2
	v_mov_b32_e32 v27, v2
	v_mov_b32_e32 v28, v2
	v_mov_b32_e32 v29, v2
	v_mov_b32_e32 v30, v2
	v_mov_b32_e32 v31, v2
	v_mov_b32_e32 v32, v2
	v_mov_b32_e32 v33, v2
	v_mov_b32_e32 v42, v2
	v_mov_b32_e32 v43, v2
	v_mov_b32_e32 v44, v2
	v_mov_b32_e32 v45, v2
	v_mov_b32_e32 v46, v2
	v_mov_b32_e32 v47, v2
	v_mov_b32_e32 v48, v2
	v_mov_b32_e32 v49, v2
	v_mov_b32_e32 v58, v2
	v_mov_b32_e32 v59, v2
	v_mov_b32_e32 v60, v2
	v_mov_b32_e32 v61, v2
	v_mov_b32_e32 v62, v2
	v_mov_b32_e32 v63, v2
	v_mov_b32_e32 v64, v2
	v_mov_b32_e32 v65, v2
	v_mov_b32_e32 v66, v2
	v_mov_b32_e32 v67, v2
	v_mov_b32_e32 v68, v2
	v_mov_b32_e32 v69, v2
	v_mov_b32_e32 v70, v2
	v_mov_b32_e32 v71, v2
	v_mov_b32_e32 v72, v2
	v_mov_b32_e32 v73, v2
	v_mov_b32_e32 v82, v2
	v_mov_b32_e32 v83, v2
	v_mov_b32_e32 v84, v2
	v_mov_b32_e32 v85, v2
	v_mov_b32_e32 v86, v2
	v_mov_b32_e32 v87, v2
	v_mov_b32_e32 v88, v2
	v_mov_b32_e32 v89, v2
	s_waitcnt vmcnt(0)
	v_mov_b32_e32 v98, v2
	v_mov_b32_e32 v99, v2
	v_mov_b32_e32 v100, v2
	v_mov_b32_e32 v101, v2
	v_mov_b32_e32 v102, v2
	v_mov_b32_e32 v103, v2
	v_mov_b32_e32 v104, v2
	v_mov_b32_e32 v105, v2
	v_mov_b32_e32 v114, v2
	v_mov_b32_e32 v115, v2
	v_mov_b32_e32 v116, v2
	v_mov_b32_e32 v117, v2
	v_mov_b32_e32 v118, v2
	v_mov_b32_e32 v119, v2
	v_mov_b32_e32 v120, v2
	v_mov_b32_e32 v121, v2
	v_mov_b32_e32 v74, v2
	v_mov_b32_e32 v75, v2
	v_mov_b32_e32 v76, v2
	v_mov_b32_e32 v77, v2
	v_mov_b32_e32 v78, v2
	v_mov_b32_e32 v79, v2
	v_mov_b32_e32 v80, v2
	v_mov_b32_e32 v81, v2
	v_mov_b32_e32 v90, v2
	v_mov_b32_e32 v91, v2
	v_mov_b32_e32 v92, v2
	v_mov_b32_e32 v93, v2
	v_mov_b32_e32 v94, v2
	v_mov_b32_e32 v95, v2
	v_mov_b32_e32 v96, v2
	v_mov_b32_e32 v97, v2
	v_mov_b32_e32 v106, v2
	v_mov_b32_e32 v107, v2
	v_mov_b32_e32 v108, v2
	v_mov_b32_e32 v109, v2
	v_mov_b32_e32 v110, v2
	v_mov_b32_e32 v111, v2
	v_mov_b32_e32 v112, v2
	v_mov_b32_e32 v113, v2
	v_mov_b32_e32 v122, v2
	v_mov_b32_e32 v123, v2
	v_mov_b32_e32 v124, v2
	v_mov_b32_e32 v125, v2
	v_mov_b32_e32 v126, v2
	v_mov_b32_e32 v127, v2
	v_mov_b32_e32 v128, v2
	v_mov_b32_e32 v129, v2
	.p2align	6
